# epilogue ssq loads hoisted (P7 SwiGLU, P2 k_nope, P9 stage B): issue all 8 per-row scalar loads at epilogue top instead of one per row behind previous stores
# speedup vs baseline: 1.0040x; 1.0040x over previous
.LBB0_631:
	s_lshl_b32 s0, s93, 8
	v_mov_b32_e32 v130, v168
	v_mov_b32_e32 v131, v135
	s_add_i32 s0, s0, s61
	s_nop 0
	v_add_u32_e32 v132, s0, v131
	v_ashrrev_i32_e32 v133, 31, v132
	v_lshl_add_u32 v150, v130, 3, s62
	v_lshl_add_u64 v[130:131], v[132:133], 2, s[8:9]
	global_load_dword v133, v[130:131], off
	global_load_dword v200, v[130:131], off offset:64
	global_load_dword v201, v[130:131], off offset:128
	global_load_dword v202, v[130:131], off offset:192
	global_load_dword v203, v[130:131], off offset:512
	global_load_dword v204, v[130:131], off offset:576
	global_load_dword v205, v[130:131], off offset:640
	global_load_dword v206, v[130:131], off offset:704
	v_ashrrev_i32_e32 v151, 31, v150
	s_waitcnt vmcnt(0) lgkmcnt(0)
	v_fmamk_f32 v133, v133, 0x3b000000, v173
	v_rsq_f32_e32 v152, v133
	s_nop 0
	v_pk_mul_f32 v[122:123], v[122:123], v[152:153] op_sel_hi:[1,0]
	v_pk_mul_f32 v[124:125], v[124:125], v[152:153] op_sel_hi:[1,0]
	v_pk_mul_f32 v[154:155], v[128:129], v[152:153] op_sel_hi:[1,0]
	v_pk_mul_f32 v[128:129], v[126:127], v[152:153] op_sel_hi:[1,0]
	v_cvt_pk_bf16_f32 v126, v122, v123
	v_mov_b64_e32 v[122:123], s[20:21]
	v_cvt_pk_bf16_f32 v127, v124, v125
	v_mad_i64_i32 v[124:125], s[0:1], v132, s88, v[122:123]
	s_mul_i32 s0, s92, 0x180
	s_ashr_i32 s1, s0, 31
	s_lshl_b64 s[0:1], s[0:1], 1
	v_cvt_pk_bf16_f32 v128, v128, v129
	v_cvt_pk_bf16_f32 v129, v154, v155
	v_lshl_add_u64 v[154:155], v[124:125], 0, s[0:1]
	v_lshlrev_b64 v[124:125], 1, v[150:151]
	v_lshl_add_u64 v[150:151], v[154:155], 0, v[124:125]
	global_store_dwordx4 v[150:151], v[126:129], off
	v_pk_mul_f32 v[120:121], v[120:121], v[152:153] op_sel_hi:[1,0]
	v_pk_mul_f32 v[118:119], v[118:119], v[152:153] op_sel_hi:[1,0]
	v_pk_mul_f32 v[126:127], v[116:117], v[152:153] op_sel_hi:[1,0]
	v_pk_mul_f32 v[116:117], v[114:115], v[152:153] op_sel_hi:[1,0]
	v_cvt_pk_bf16_f32 v114, v118, v119
	v_cvt_pk_bf16_f32 v115, v120, v121
	s_nop 0
	v_cvt_pk_bf16_f32 v116, v116, v117
	v_cvt_pk_bf16_f32 v117, v126, v127
	global_store_dwordx4 v[150:151], v[114:117], off offset:384
	s_nop 0
	s_nop 0
	v_add_u32_e32 v115, 16, v132
	v_mov_b32_e32 v114, v200
	v_fmamk_f32 v114, v114, 0x3b000000, v173
	v_rsq_f32_e32 v114, v114
	s_nop 0
	v_pk_mul_f32 v[110:111], v[110:111], v[114:115] op_sel_hi:[1,0]
	v_pk_mul_f32 v[116:117], v[108:109], v[114:115] op_sel_hi:[1,0]
	v_pk_mul_f32 v[108:109], v[106:107], v[114:115] op_sel_hi:[1,0]
	v_cvt_pk_bf16_f32 v106, v110, v111
	v_mad_i64_i32 v[110:111], s[44:45], v115, s88, v[122:123]
	v_lshl_add_u64 v[110:111], v[110:111], 0, s[0:1]
	v_pk_mul_f32 v[112:113], v[112:113], v[114:115] op_sel_hi:[1,0]
	v_lshl_add_u64 v[110:111], v[110:111], 0, v[124:125]
	v_cvt_pk_bf16_f32 v107, v112, v113
	v_cvt_pk_bf16_f32 v108, v108, v109
	v_cvt_pk_bf16_f32 v109, v116, v117
	global_store_dwordx4 v[110:111], v[106:109], off
	v_pk_mul_f32 v[104:105], v[104:105], v[114:115] op_sel_hi:[1,0]
	v_pk_mul_f32 v[102:103], v[102:103], v[114:115] op_sel_hi:[1,0]
	v_pk_mul_f32 v[106:107], v[100:101], v[114:115] op_sel_hi:[1,0]
	v_pk_mul_f32 v[100:101], v[98:99], v[114:115] op_sel_hi:[1,0]
	v_cvt_pk_bf16_f32 v98, v102, v103
	v_cvt_pk_bf16_f32 v99, v104, v105
	s_nop 0
	v_cvt_pk_bf16_f32 v100, v100, v101
	v_cvt_pk_bf16_f32 v101, v106, v107
	global_store_dwordx4 v[110:111], v[98:101], off offset:384
	s_nop 0
	s_nop 0
	v_add_u32_e32 v99, 32, v132
	v_mov_b32_e32 v98, v201
	v_fmamk_f32 v98, v98, 0x3b000000, v173
	v_rsq_f32_e32 v98, v98
	s_nop 0
	v_pk_mul_f32 v[94:95], v[94:95], v[98:99] op_sel_hi:[1,0]
	v_pk_mul_f32 v[100:101], v[92:93], v[98:99] op_sel_hi:[1,0]
	v_pk_mul_f32 v[92:93], v[90:91], v[98:99] op_sel_hi:[1,0]
	v_cvt_pk_bf16_f32 v90, v94, v95
	v_mad_i64_i32 v[94:95], s[44:45], v99, s88, v[122:123]
	v_lshl_add_u64 v[94:95], v[94:95], 0, s[0:1]
	v_pk_mul_f32 v[96:97], v[96:97], v[98:99] op_sel_hi:[1,0]
	v_lshl_add_u64 v[94:95], v[94:95], 0, v[124:125]
	v_cvt_pk_bf16_f32 v91, v96, v97
	v_cvt_pk_bf16_f32 v92, v92, v93
	v_cvt_pk_bf16_f32 v93, v100, v101
	global_store_dwordx4 v[94:95], v[90:93], off
	v_pk_mul_f32 v[88:89], v[88:89], v[98:99] op_sel_hi:[1,0]
	v_pk_mul_f32 v[86:87], v[86:87], v[98:99] op_sel_hi:[1,0]
	v_pk_mul_f32 v[90:91], v[84:85], v[98:99] op_sel_hi:[1,0]
	v_pk_mul_f32 v[84:85], v[82:83], v[98:99] op_sel_hi:[1,0]
	v_cvt_pk_bf16_f32 v82, v86, v87
	v_cvt_pk_bf16_f32 v83, v88, v89
	s_nop 0
	v_cvt_pk_bf16_f32 v84, v84, v85
	v_cvt_pk_bf16_f32 v85, v90, v91
	global_store_dwordx4 v[94:95], v[82:85], off offset:384
	s_nop 0
	s_nop 0
	v_add_u32_e32 v83, 48, v132
	v_mov_b32_e32 v82, v202
	v_fmamk_f32 v82, v82, 0x3b000000, v173
	v_rsq_f32_e32 v82, v82
	s_nop 0
	v_pk_mul_f32 v[78:79], v[78:79], v[82:83] op_sel_hi:[1,0]
	v_pk_mul_f32 v[84:85], v[76:77], v[82:83] op_sel_hi:[1,0]
	v_pk_mul_f32 v[76:77], v[74:75], v[82:83] op_sel_hi:[1,0]
	v_cvt_pk_bf16_f32 v74, v78, v79
	v_mad_i64_i32 v[78:79], s[44:45], v83, s88, v[122:123]
	v_lshl_add_u64 v[78:79], v[78:79], 0, s[0:1]
	v_pk_mul_f32 v[80:81], v[80:81], v[82:83] op_sel_hi:[1,0]
	v_lshl_add_u64 v[78:79], v[78:79], 0, v[124:125]
	v_cvt_pk_bf16_f32 v75, v80, v81
	v_cvt_pk_bf16_f32 v76, v76, v77
	v_cvt_pk_bf16_f32 v77, v84, v85
	global_store_dwordx4 v[78:79], v[74:77], off
	v_pk_mul_f32 v[72:73], v[72:73], v[82:83] op_sel_hi:[1,0]
	v_pk_mul_f32 v[70:71], v[70:71], v[82:83] op_sel_hi:[1,0]
	v_pk_mul_f32 v[74:75], v[68:69], v[82:83] op_sel_hi:[1,0]
	v_pk_mul_f32 v[68:69], v[66:67], v[82:83] op_sel_hi:[1,0]
	v_cvt_pk_bf16_f32 v66, v70, v71
	v_cvt_pk_bf16_f32 v67, v72, v73
	s_nop 0
	v_cvt_pk_bf16_f32 v68, v68, v69
	v_cvt_pk_bf16_f32 v69, v74, v75
	global_store_dwordx4 v[78:79], v[66:69], off offset:384
	s_nop 0
	s_nop 0
	v_add_u32_e32 v67, 0x80, v132
	v_mov_b32_e32 v66, v203
	v_fmamk_f32 v66, v66, 0x3b000000, v173
	v_rsq_f32_e32 v66, v66
	s_nop 0
	v_pk_mul_f32 v[62:63], v[62:63], v[66:67] op_sel_hi:[1,0]
	v_pk_mul_f32 v[68:69], v[60:61], v[66:67] op_sel_hi:[1,0]
	v_pk_mul_f32 v[60:61], v[58:59], v[66:67] op_sel_hi:[1,0]
	v_cvt_pk_bf16_f32 v58, v62, v63
	v_mad_i64_i32 v[62:63], s[44:45], v67, s88, v[122:123]
	v_lshl_add_u64 v[62:63], v[62:63], 0, s[0:1]
	v_pk_mul_f32 v[64:65], v[64:65], v[66:67] op_sel_hi:[1,0]
	v_lshl_add_u64 v[62:63], v[62:63], 0, v[124:125]
	v_cvt_pk_bf16_f32 v59, v64, v65
	v_cvt_pk_bf16_f32 v60, v60, v61
	v_cvt_pk_bf16_f32 v61, v68, v69
	global_store_dwordx4 v[62:63], v[58:61], off
	v_pk_mul_f32 v[56:57], v[56:57], v[66:67] op_sel_hi:[1,0]
	v_pk_mul_f32 v[54:55], v[54:55], v[66:67] op_sel_hi:[1,0]
	v_pk_mul_f32 v[58:59], v[52:53], v[66:67] op_sel_hi:[1,0]
	v_pk_mul_f32 v[52:53], v[50:51], v[66:67] op_sel_hi:[1,0]
	v_cvt_pk_bf16_f32 v50, v54, v55
	v_cvt_pk_bf16_f32 v51, v56, v57
	s_nop 0
	v_cvt_pk_bf16_f32 v52, v52, v53
	v_cvt_pk_bf16_f32 v53, v58, v59
	global_store_dwordx4 v[62:63], v[50:53], off offset:384
	s_nop 0
	s_nop 0
	v_add_u32_e32 v51, 0x90, v132
	v_mov_b32_e32 v50, v204
	v_fmamk_f32 v50, v50, 0x3b000000, v173
	v_rsq_f32_e32 v50, v50
	s_nop 0
	v_pk_mul_f32 v[46:47], v[46:47], v[50:51] op_sel_hi:[1,0]
	v_pk_mul_f32 v[52:53], v[44:45], v[50:51] op_sel_hi:[1,0]
	v_pk_mul_f32 v[44:45], v[42:43], v[50:51] op_sel_hi:[1,0]
	v_cvt_pk_bf16_f32 v42, v46, v47
	v_mad_i64_i32 v[46:47], s[44:45], v51, s88, v[122:123]
	v_lshl_add_u64 v[46:47], v[46:47], 0, s[0:1]
	v_pk_mul_f32 v[48:49], v[48:49], v[50:51] op_sel_hi:[1,0]
	v_lshl_add_u64 v[46:47], v[46:47], 0, v[124:125]
	v_cvt_pk_bf16_f32 v43, v48, v49
	v_cvt_pk_bf16_f32 v44, v44, v45
	v_cvt_pk_bf16_f32 v45, v52, v53
	global_store_dwordx4 v[46:47], v[42:45], off
	v_pk_mul_f32 v[40:41], v[40:41], v[50:51] op_sel_hi:[1,0]
	v_pk_mul_f32 v[38:39], v[38:39], v[50:51] op_sel_hi:[1,0]
	v_pk_mul_f32 v[42:43], v[36:37], v[50:51] op_sel_hi:[1,0]
	v_pk_mul_f32 v[36:37], v[34:35], v[50:51] op_sel_hi:[1,0]
	v_cvt_pk_bf16_f32 v34, v38, v39
	v_cvt_pk_bf16_f32 v35, v40, v41
	s_nop 0
	v_cvt_pk_bf16_f32 v36, v36, v37
	v_cvt_pk_bf16_f32 v37, v42, v43
	global_store_dwordx4 v[46:47], v[34:37], off offset:384
	s_nop 0
	s_nop 0
	v_add_u32_e32 v35, 0xa0, v132
	v_mov_b32_e32 v34, v205
	v_fmamk_f32 v34, v34, 0x3b000000, v173
	v_rsq_f32_e32 v34, v34
	s_nop 0
	v_pk_mul_f32 v[30:31], v[30:31], v[34:35] op_sel_hi:[1,0]
	v_pk_mul_f32 v[36:37], v[28:29], v[34:35] op_sel_hi:[1,0]
	v_pk_mul_f32 v[28:29], v[26:27], v[34:35] op_sel_hi:[1,0]
	v_cvt_pk_bf16_f32 v26, v30, v31
	v_mad_i64_i32 v[30:31], s[44:45], v35, s88, v[122:123]
	v_lshl_add_u64 v[30:31], v[30:31], 0, s[0:1]
	v_pk_mul_f32 v[32:33], v[32:33], v[34:35] op_sel_hi:[1,0]
	v_lshl_add_u64 v[30:31], v[30:31], 0, v[124:125]
	v_cvt_pk_bf16_f32 v27, v32, v33
	v_cvt_pk_bf16_f32 v28, v28, v29
	v_cvt_pk_bf16_f32 v29, v36, v37
	global_store_dwordx4 v[30:31], v[26:29], off
	v_pk_mul_f32 v[24:25], v[24:25], v[34:35] op_sel_hi:[1,0]
	v_pk_mul_f32 v[22:23], v[22:23], v[34:35] op_sel_hi:[1,0]
	v_pk_mul_f32 v[26:27], v[20:21], v[34:35] op_sel_hi:[1,0]
	v_pk_mul_f32 v[20:21], v[18:19], v[34:35] op_sel_hi:[1,0]
	v_cvt_pk_bf16_f32 v18, v22, v23
	v_cvt_pk_bf16_f32 v19, v24, v25
	s_nop 0
	v_cvt_pk_bf16_f32 v20, v20, v21
	v_cvt_pk_bf16_f32 v21, v26, v27
	global_store_dwordx4 v[30:31], v[18:21], off offset:384
	s_nop 0
	s_nop 0
	v_add_u32_e32 v19, 0xb0, v132
	v_mov_b32_e32 v18, v206
	v_fmamk_f32 v18, v18, 0x3b000000, v173
	v_rsq_f32_e32 v18, v18
	s_nop 0
	v_pk_mul_f32 v[14:15], v[14:15], v[18:19] op_sel_hi:[1,0]
	v_pk_mul_f32 v[20:21], v[12:13], v[18:19] op_sel_hi:[1,0]
	v_pk_mul_f32 v[12:13], v[10:11], v[18:19] op_sel_hi:[1,0]
	v_cvt_pk_bf16_f32 v10, v14, v15
	v_mad_i64_i32 v[14:15], s[44:45], v19, s88, v[122:123]
	v_lshl_add_u64 v[14:15], v[14:15], 0, s[0:1]
	v_lshl_add_u64 v[14:15], v[14:15], 0, v[124:125]
	s_mov_b64 s[0:1], 0x180
	v_lshl_add_u64 v[150:151], v[14:15], 0, s[0:1]
	v_pk_mul_f32 v[16:17], v[16:17], v[18:19] op_sel_hi:[1,0]
	v_pk_mul_f32 v[8:9], v[8:9], v[18:19] op_sel_hi:[1,0]
	v_cvt_pk_bf16_f32 v11, v16, v17
	v_cvt_pk_bf16_f32 v12, v12, v13
	v_cvt_pk_bf16_f32 v13, v20, v21
	global_store_dwordx4 v[14:15], v[10:13], off
	v_pk_mul_f32 v[6:7], v[6:7], v[18:19] op_sel_hi:[1,0]
	v_pk_mul_f32 v[4:5], v[4:5], v[18:19] op_sel_hi:[1,0]
	v_pk_mul_f32 v[2:3], v[2:3], v[18:19] op_sel_hi:[1,0]
	v_cvt_pk_bf16_f32 v130, v6, v7
	v_cvt_pk_bf16_f32 v131, v8, v9
	s_nop 0
	v_cvt_pk_bf16_f32 v132, v2, v3
	v_cvt_pk_bf16_f32 v133, v4, v5

.LBB0_1202:
	s_lshl_b32 s36, s71, 8
	v_mov_b32_e32 v146, v151
	v_mov_b32_e32 v144, v150
	s_add_i32 s36, s36, s59
	v_mov_b32_e32 v158, v118
	v_add_u32_e32 v148, s36, v144
	v_ashrrev_i32_e32 v149, 31, v148
	v_lshl_add_u64 v[144:145], v[148:149], 2, s[14:15]
	global_load_dword v149, v[144:145], off
	global_load_dword v200, v[144:145], off offset:64
	global_load_dword v201, v[144:145], off offset:128
	global_load_dword v202, v[144:145], off offset:192
	global_load_dword v203, v[144:145], off offset:512
	global_load_dword v204, v[144:145], off offset:576
	global_load_dword v205, v[144:145], off offset:640
	global_load_dword v206, v[144:145], off offset:704
	v_mov_b32_e32 v118, v116
	v_mov_b32_e32 v160, v114
	v_mov_b32_e32 v114, v120
	v_add_u32_e32 v164, 16, v148
	v_ashrrev_i32_e32 v165, 31, v164
	v_lshl_add_u64 v[166:167], v[164:165], 2, s[14:15]
	s_lshl_b32 s36, s70, 7
	v_mov_b64_e32 v[144:145], s[16:17]
	s_ashr_i32 s37, s36, 31
	v_lshl_add_u32 v146, v146, 3, s60
	s_lshl_b64 s[36:37], s[36:37], 1
	v_ashrrev_i32_e32 v147, 31, v146
	v_mad_i64_i32 v[162:163], s[38:39], v148, s65, v[144:145]
	v_lshl_add_u64 v[162:163], v[162:163], 0, s[36:37]
	v_lshlrev_b64 v[146:147], 1, v[146:147]
	v_lshl_add_u64 v[162:163], v[162:163], 0, v[146:147]
	s_and_b64 vcc, exec, s[0:1]
	s_waitcnt vmcnt(0) lgkmcnt(0)
	v_fmamk_f32 v116, v149, 0x3a000000, v156
	v_rsq_f32_e32 v120, v116
	s_nop 0
	v_pk_mul_f32 v[122:123], v[122:123], v[120:121] op_sel_hi:[1,0]
	s_nop 0
	v_mul_f32_e32 v116, 0xbfb8aa3b, v122
	v_exp_f32_e32 v116, v116
	v_pk_mul_f32 v[126:127], v[126:127], v[120:121] op_sel_hi:[1,0]
	v_pk_mul_f32 v[124:125], v[124:125], v[120:121] op_sel_hi:[1,0]
	v_mul_f32_e32 v149, 0xbfb8aa3b, v126
	v_exp_f32_e32 v149, v149
	v_add_f32_e32 v116, 1.0, v116
	v_pk_mul_f32 v[128:129], v[128:129], v[120:121] op_sel_hi:[1,0]
	v_mov_b32_e32 v161, v126
	v_mov_b32_e32 v126, v115
	v_mul_f32_e32 v168, 0xbfb8aa3b, v124
	v_mov_b32_e32 v115, v124
	v_mov_b32_e32 v124, v121
	v_rcp_f32_e32 v121, v116
	v_mul_f32_e32 v157, 0xbfb8aa3b, v123
	v_mov_b32_e32 v159, v122
	v_exp_f32_e32 v157, v157
	v_add_f32_e32 v149, 1.0, v149
	v_mov_b32_e32 v122, v119
	v_mul_f32_e32 v169, 0xbfb8aa3b, v128
	v_mov_b32_e32 v119, v128
	v_mov_b32_e32 v128, v117
	v_pk_mul_f32 v[116:117], v[158:159], v[120:121]
	v_rcp_f32_e32 v121, v149
	v_mul_f32_e32 v165, 0xbfb8aa3b, v127
	v_exp_f32_e32 v149, v165
	v_add_f32_e32 v157, 1.0, v157
	v_pk_mul_f32 v[158:159], v[160:161], v[120:121]
	v_rcp_f32_e32 v121, v157
	v_exp_f32_e32 v165, v168
	v_add_f32_e32 v149, 1.0, v149
	v_exp_f32_e32 v157, v169
	v_pk_mul_f32 v[122:123], v[122:123], v[120:121]
	v_rcp_f32_e32 v121, v149
	v_add_f32_e32 v161, 1.0, v165
	v_mul_f32_e32 v170, 0xbfb8aa3b, v125
	v_exp_f32_e32 v160, v170
	v_pk_mul_f32 v[126:127], v[126:127], v[120:121]
	v_rcp_f32_e32 v121, v161
	v_add_f32_e32 v157, 1.0, v157
	v_mul_f32_e32 v161, v116, v117
	v_mul_f32_e32 v171, 0xbfb8aa3b, v129
	v_pk_mul_f32 v[116:117], v[114:115], v[120:121]
	v_rcp_f32_e32 v121, v157
	v_exp_f32_e32 v149, v171
	v_add_f32_e32 v160, 1.0, v160
	v_mul_f32_e32 v115, v116, v117
	v_pk_mul_f32 v[118:119], v[118:119], v[120:121]
	v_rcp_f32_e32 v121, v160
	v_add_f32_e32 v149, 1.0, v149
	v_mul_f32_e32 v114, v122, v123
	v_mul_f32_e32 v123, v118, v119
	v_pk_mul_f32 v[116:117], v[124:125], v[120:121]
	v_rcp_f32_e32 v121, v149
	v_mul_f32_e32 v116, v116, v117
	v_mul_f32_e32 v157, v158, v159
	v_cvt_pk_bf16_f32 v114, v161, v114
	v_pk_mul_f32 v[118:119], v[128:129], v[120:121]
	v_mul_f32_e32 v122, v126, v127
	v_mul_f32_e32 v117, v118, v119
	v_cvt_pk_bf16_f32 v115, v115, v116
	v_cvt_pk_bf16_f32 v116, v157, v122
	v_cvt_pk_bf16_f32 v117, v123, v117
	global_store_dwordx4 v[162:163], v[114:117], off
	s_nop 0
	v_add_u32_e32 v118, 32, v148
	v_mov_b32_e32 v114, v102
	v_mov_b32_e32 v102, v100
	v_mov_b32_e32 v116, v98
	v_mov_b32_e32 v98, v104
	v_ashrrev_i32_e32 v119, 31, v118
	v_lshl_add_u64 v[122:123], v[118:119], 2, s[14:15]
	v_mad_i64_i32 v[120:121], s[38:39], v164, s65, v[144:145]
	v_lshl_add_u64 v[120:121], v[120:121], 0, s[36:37]
	v_lshl_add_u64 v[120:121], v[120:121], 0, v[146:147]
	v_mov_b32_e32 v115, v200
	v_fmamk_f32 v100, v115, 0x3a000000, v156
	v_rsq_f32_e32 v104, v100
	s_nop 0
	v_pk_mul_f32 v[110:111], v[110:111], v[104:105] op_sel_hi:[1,0]
	s_nop 0
	v_mul_f32_e32 v100, 0xbfb8aa3b, v110
	v_exp_f32_e32 v100, v100
	v_pk_mul_f32 v[106:107], v[106:107], v[104:105] op_sel_hi:[1,0]
	v_pk_mul_f32 v[112:113], v[112:113], v[104:105] op_sel_hi:[1,0]
	v_mul_f32_e32 v119, 0xbfb8aa3b, v106
	v_exp_f32_e32 v119, v119
	v_add_f32_e32 v100, 1.0, v100
	v_pk_mul_f32 v[108:109], v[108:109], v[104:105] op_sel_hi:[1,0]
	v_mov_b32_e32 v117, v106
	v_mov_b32_e32 v106, v99
	v_mul_f32_e32 v126, 0xbfb8aa3b, v112
	v_mov_b32_e32 v99, v112
	v_mov_b32_e32 v112, v105
	v_rcp_f32_e32 v105, v100
	v_mul_f32_e32 v124, 0xbfb8aa3b, v111
	v_mov_b32_e32 v115, v110
	v_exp_f32_e32 v124, v124
	v_add_f32_e32 v119, 1.0, v119
	v_mov_b32_e32 v110, v103
	v_mul_f32_e32 v127, 0xbfb8aa3b, v108
	v_mov_b32_e32 v103, v108
	v_mov_b32_e32 v108, v101
	v_pk_mul_f32 v[100:101], v[114:115], v[104:105]
	v_rcp_f32_e32 v105, v119
	v_mul_f32_e32 v125, 0xbfb8aa3b, v107
	v_exp_f32_e32 v119, v125
	v_add_f32_e32 v124, 1.0, v124
	v_pk_mul_f32 v[114:115], v[116:117], v[104:105]
	v_rcp_f32_e32 v105, v124
	v_exp_f32_e32 v125, v126
	v_add_f32_e32 v119, 1.0, v119
	v_exp_f32_e32 v116, v127
	v_pk_mul_f32 v[110:111], v[110:111], v[104:105]
	v_rcp_f32_e32 v105, v119
	v_add_f32_e32 v124, 1.0, v125
	v_mul_f32_e32 v128, 0xbfb8aa3b, v113
	v_exp_f32_e32 v117, v128
	v_pk_mul_f32 v[106:107], v[106:107], v[104:105]
	v_rcp_f32_e32 v105, v124
	v_add_f32_e32 v116, 1.0, v116
	v_mul_f32_e32 v124, v100, v101
	v_mul_f32_e32 v129, 0xbfb8aa3b, v109
	v_pk_mul_f32 v[100:101], v[98:99], v[104:105]
	v_rcp_f32_e32 v105, v116
	v_exp_f32_e32 v119, v129
	v_add_f32_e32 v117, 1.0, v117
	v_mul_f32_e32 v99, v100, v101
	v_pk_mul_f32 v[102:103], v[102:103], v[104:105]
	v_rcp_f32_e32 v105, v117
	v_add_f32_e32 v119, 1.0, v119
	v_mul_f32_e32 v106, v106, v107
	v_mul_f32_e32 v107, v102, v103
	v_pk_mul_f32 v[100:101], v[112:113], v[104:105]
	v_rcp_f32_e32 v105, v119
	v_mul_f32_e32 v98, v110, v111
	v_mul_f32_e32 v100, v100, v101
	v_mul_f32_e32 v114, v114, v115
	v_pk_mul_f32 v[102:103], v[108:109], v[104:105]
	v_cvt_pk_bf16_f32 v98, v124, v98
	v_cvt_pk_bf16_f32 v99, v99, v100
	v_cvt_pk_bf16_f32 v100, v114, v106
	v_mad_i64_i32 v[104:105], s[38:39], v118, s65, v[144:145]
	v_mul_f32_e32 v101, v102, v103
	v_cvt_pk_bf16_f32 v101, v107, v101
	global_store_dwordx4 v[120:121], v[98:101], off
	s_nop 0
	v_add_u32_e32 v102, 48, v148
	v_mov_b32_e32 v98, v86
	v_mov_b32_e32 v86, v84
	v_mov_b32_e32 v100, v82
	v_mov_b32_e32 v82, v88
	v_ashrrev_i32_e32 v103, 31, v102
	v_lshl_add_u64 v[106:107], v[102:103], 2, s[14:15]
	v_lshl_add_u64 v[104:105], v[104:105], 0, s[36:37]
	v_lshl_add_u64 v[104:105], v[104:105], 0, v[146:147]
	v_mov_b32_e32 v99, v201
	v_fmamk_f32 v84, v99, 0x3a000000, v156
	v_rsq_f32_e32 v88, v84
	s_nop 0
	v_pk_mul_f32 v[94:95], v[94:95], v[88:89] op_sel_hi:[1,0]
	s_nop 0
	v_mul_f32_e32 v84, 0xbfb8aa3b, v94
	v_exp_f32_e32 v84, v84
	v_pk_mul_f32 v[90:91], v[90:91], v[88:89] op_sel_hi:[1,0]
	v_pk_mul_f32 v[96:97], v[96:97], v[88:89] op_sel_hi:[1,0]
	v_mul_f32_e32 v103, 0xbfb8aa3b, v90
	v_exp_f32_e32 v103, v103
	v_add_f32_e32 v84, 1.0, v84
	v_pk_mul_f32 v[92:93], v[92:93], v[88:89] op_sel_hi:[1,0]
	v_mov_b32_e32 v101, v90
	v_mov_b32_e32 v90, v83
	v_mul_f32_e32 v110, 0xbfb8aa3b, v96
	v_mov_b32_e32 v83, v96
	v_mov_b32_e32 v96, v89
	v_rcp_f32_e32 v89, v84
	v_mul_f32_e32 v108, 0xbfb8aa3b, v95
	v_mov_b32_e32 v99, v94
	v_exp_f32_e32 v108, v108
	v_add_f32_e32 v103, 1.0, v103
	v_mov_b32_e32 v94, v87
	v_mul_f32_e32 v111, 0xbfb8aa3b, v92
	v_mov_b32_e32 v87, v92
	v_mov_b32_e32 v92, v85
	v_pk_mul_f32 v[84:85], v[98:99], v[88:89]
	v_rcp_f32_e32 v89, v103
	v_mul_f32_e32 v109, 0xbfb8aa3b, v91
	v_exp_f32_e32 v103, v109
	v_add_f32_e32 v108, 1.0, v108
	v_pk_mul_f32 v[98:99], v[100:101], v[88:89]
	v_rcp_f32_e32 v89, v108
	v_exp_f32_e32 v109, v110
	v_add_f32_e32 v103, 1.0, v103
	v_exp_f32_e32 v100, v111
	v_pk_mul_f32 v[94:95], v[94:95], v[88:89]
	v_rcp_f32_e32 v89, v103
	v_add_f32_e32 v108, 1.0, v109
	v_mul_f32_e32 v112, 0xbfb8aa3b, v97
	v_exp_f32_e32 v101, v112
	v_pk_mul_f32 v[90:91], v[90:91], v[88:89]
	v_rcp_f32_e32 v89, v108
	v_add_f32_e32 v100, 1.0, v100
	v_mul_f32_e32 v108, v84, v85
	v_mul_f32_e32 v113, 0xbfb8aa3b, v93
	v_pk_mul_f32 v[84:85], v[82:83], v[88:89]
	v_rcp_f32_e32 v89, v100
	v_exp_f32_e32 v103, v113
	v_add_f32_e32 v101, 1.0, v101
	v_mul_f32_e32 v83, v84, v85
	v_pk_mul_f32 v[86:87], v[86:87], v[88:89]
	v_rcp_f32_e32 v89, v101
	v_add_f32_e32 v103, 1.0, v103
	v_mul_f32_e32 v90, v90, v91
	v_mul_f32_e32 v91, v86, v87
	v_pk_mul_f32 v[84:85], v[96:97], v[88:89]
	v_rcp_f32_e32 v89, v103
	v_mul_f32_e32 v82, v94, v95
	v_mul_f32_e32 v84, v84, v85
	v_mul_f32_e32 v98, v98, v99
	v_pk_mul_f32 v[86:87], v[92:93], v[88:89]
	v_cvt_pk_bf16_f32 v82, v108, v82
	v_cvt_pk_bf16_f32 v83, v83, v84
	v_cvt_pk_bf16_f32 v84, v98, v90
	v_mad_i64_i32 v[88:89], s[38:39], v102, s65, v[144:145]
	v_mul_f32_e32 v85, v86, v87
	v_cvt_pk_bf16_f32 v85, v91, v85
	global_store_dwordx4 v[104:105], v[82:85], off
	s_nop 0
	v_add_u32_e32 v86, 0x80, v148
	v_mov_b32_e32 v82, v70
	v_mov_b32_e32 v70, v68
	v_mov_b32_e32 v84, v66
	v_mov_b32_e32 v66, v72
	v_ashrrev_i32_e32 v87, 31, v86
	v_lshl_add_u64 v[90:91], v[86:87], 2, s[14:15]
	v_lshl_add_u64 v[88:89], v[88:89], 0, s[36:37]
	v_lshl_add_u64 v[88:89], v[88:89], 0, v[146:147]
	v_mov_b32_e32 v83, v202
	v_fmamk_f32 v68, v83, 0x3a000000, v156
	v_rsq_f32_e32 v72, v68
	s_nop 0
	v_pk_mul_f32 v[78:79], v[78:79], v[72:73] op_sel_hi:[1,0]
	s_nop 0
	v_mul_f32_e32 v68, 0xbfb8aa3b, v78
	v_exp_f32_e32 v68, v68
	v_pk_mul_f32 v[74:75], v[74:75], v[72:73] op_sel_hi:[1,0]
	v_pk_mul_f32 v[80:81], v[80:81], v[72:73] op_sel_hi:[1,0]
	v_mul_f32_e32 v87, 0xbfb8aa3b, v74
	v_exp_f32_e32 v87, v87
	v_add_f32_e32 v68, 1.0, v68
	v_pk_mul_f32 v[76:77], v[76:77], v[72:73] op_sel_hi:[1,0]
	v_mov_b32_e32 v85, v74
	v_mov_b32_e32 v74, v67
	v_mul_f32_e32 v94, 0xbfb8aa3b, v80
	v_mov_b32_e32 v67, v80
	v_mov_b32_e32 v80, v73
	v_rcp_f32_e32 v73, v68
	v_mul_f32_e32 v92, 0xbfb8aa3b, v79
	v_mov_b32_e32 v83, v78
	v_exp_f32_e32 v92, v92
	v_add_f32_e32 v87, 1.0, v87
	v_mov_b32_e32 v78, v71
	v_mul_f32_e32 v95, 0xbfb8aa3b, v76
	v_mov_b32_e32 v71, v76
	v_mov_b32_e32 v76, v69
	v_pk_mul_f32 v[68:69], v[82:83], v[72:73]
	v_rcp_f32_e32 v73, v87
	v_mul_f32_e32 v93, 0xbfb8aa3b, v75
	v_exp_f32_e32 v87, v93
	v_add_f32_e32 v92, 1.0, v92
	v_pk_mul_f32 v[82:83], v[84:85], v[72:73]
	v_rcp_f32_e32 v73, v92
	v_exp_f32_e32 v93, v94
	v_add_f32_e32 v87, 1.0, v87
	v_exp_f32_e32 v84, v95
	v_pk_mul_f32 v[78:79], v[78:79], v[72:73]
	v_rcp_f32_e32 v73, v87
	v_add_f32_e32 v92, 1.0, v93
	v_mul_f32_e32 v96, 0xbfb8aa3b, v81
	v_exp_f32_e32 v85, v96
	v_pk_mul_f32 v[74:75], v[74:75], v[72:73]
	v_rcp_f32_e32 v73, v92
	v_add_f32_e32 v84, 1.0, v84
	v_mul_f32_e32 v92, v68, v69
	v_mul_f32_e32 v97, 0xbfb8aa3b, v77
	v_pk_mul_f32 v[68:69], v[66:67], v[72:73]
	v_rcp_f32_e32 v73, v84
	v_exp_f32_e32 v87, v97
	v_add_f32_e32 v85, 1.0, v85
	v_mul_f32_e32 v67, v68, v69
	v_pk_mul_f32 v[70:71], v[70:71], v[72:73]
	v_rcp_f32_e32 v73, v85
	v_add_f32_e32 v87, 1.0, v87
	v_mul_f32_e32 v74, v74, v75
	v_mul_f32_e32 v75, v70, v71
	v_pk_mul_f32 v[68:69], v[80:81], v[72:73]
	v_rcp_f32_e32 v73, v87
	v_mul_f32_e32 v66, v78, v79
	v_mul_f32_e32 v68, v68, v69
	v_mul_f32_e32 v82, v82, v83
	v_pk_mul_f32 v[70:71], v[76:77], v[72:73]
	v_cvt_pk_bf16_f32 v66, v92, v66
	v_cvt_pk_bf16_f32 v67, v67, v68
	v_cvt_pk_bf16_f32 v68, v82, v74
	v_mad_i64_i32 v[72:73], s[38:39], v86, s65, v[144:145]
	v_mul_f32_e32 v69, v70, v71
	v_cvt_pk_bf16_f32 v69, v75, v69
	global_store_dwordx4 v[88:89], v[66:69], off
	s_nop 0
	v_add_u32_e32 v70, 0x90, v148
	v_mov_b32_e32 v66, v54
	v_mov_b32_e32 v54, v52
	v_mov_b32_e32 v68, v50
	v_mov_b32_e32 v50, v56
	v_ashrrev_i32_e32 v71, 31, v70
	v_lshl_add_u64 v[74:75], v[70:71], 2, s[14:15]
	v_lshl_add_u64 v[72:73], v[72:73], 0, s[36:37]
	v_lshl_add_u64 v[72:73], v[72:73], 0, v[146:147]
	v_mov_b32_e32 v67, v203
	v_fmamk_f32 v52, v67, 0x3a000000, v156
	v_rsq_f32_e32 v56, v52
	s_nop 0
	v_pk_mul_f32 v[62:63], v[62:63], v[56:57] op_sel_hi:[1,0]
	s_nop 0
	v_mul_f32_e32 v52, 0xbfb8aa3b, v62
	v_exp_f32_e32 v52, v52
	v_pk_mul_f32 v[58:59], v[58:59], v[56:57] op_sel_hi:[1,0]
	v_pk_mul_f32 v[64:65], v[64:65], v[56:57] op_sel_hi:[1,0]
	v_mul_f32_e32 v71, 0xbfb8aa3b, v58
	v_exp_f32_e32 v71, v71
	v_add_f32_e32 v52, 1.0, v52
	v_pk_mul_f32 v[60:61], v[60:61], v[56:57] op_sel_hi:[1,0]
	v_mov_b32_e32 v69, v58
	v_mov_b32_e32 v58, v51
	v_mul_f32_e32 v78, 0xbfb8aa3b, v64
	v_mov_b32_e32 v51, v64
	v_mov_b32_e32 v64, v57
	v_rcp_f32_e32 v57, v52
	v_mul_f32_e32 v76, 0xbfb8aa3b, v63
	v_mov_b32_e32 v67, v62
	v_exp_f32_e32 v76, v76
	v_add_f32_e32 v71, 1.0, v71
	v_mov_b32_e32 v62, v55
	v_mul_f32_e32 v79, 0xbfb8aa3b, v60
	v_mov_b32_e32 v55, v60
	v_mov_b32_e32 v60, v53
	v_pk_mul_f32 v[52:53], v[66:67], v[56:57]
	v_rcp_f32_e32 v57, v71
	v_mul_f32_e32 v77, 0xbfb8aa3b, v59
	v_exp_f32_e32 v71, v77
	v_add_f32_e32 v76, 1.0, v76
	v_pk_mul_f32 v[66:67], v[68:69], v[56:57]
	v_rcp_f32_e32 v57, v76
	v_exp_f32_e32 v77, v78
	v_add_f32_e32 v71, 1.0, v71
	v_exp_f32_e32 v68, v79
	v_pk_mul_f32 v[62:63], v[62:63], v[56:57]
	v_rcp_f32_e32 v57, v71
	v_add_f32_e32 v76, 1.0, v77
	v_mul_f32_e32 v80, 0xbfb8aa3b, v65
	v_exp_f32_e32 v69, v80
	v_pk_mul_f32 v[58:59], v[58:59], v[56:57]
	v_rcp_f32_e32 v57, v76
	v_add_f32_e32 v68, 1.0, v68
	v_mul_f32_e32 v76, v52, v53
	v_mul_f32_e32 v81, 0xbfb8aa3b, v61
	v_pk_mul_f32 v[52:53], v[50:51], v[56:57]
	v_rcp_f32_e32 v57, v68
	v_exp_f32_e32 v71, v81
	v_add_f32_e32 v69, 1.0, v69
	v_mul_f32_e32 v51, v52, v53
	v_pk_mul_f32 v[54:55], v[54:55], v[56:57]
	v_rcp_f32_e32 v57, v69
	v_add_f32_e32 v71, 1.0, v71
	v_mul_f32_e32 v58, v58, v59
	v_mul_f32_e32 v59, v54, v55
	v_pk_mul_f32 v[52:53], v[64:65], v[56:57]
	v_rcp_f32_e32 v57, v71
	v_mul_f32_e32 v50, v62, v63
	v_mul_f32_e32 v52, v52, v53
	v_mul_f32_e32 v66, v66, v67
	v_pk_mul_f32 v[54:55], v[60:61], v[56:57]
	v_cvt_pk_bf16_f32 v50, v76, v50
	v_cvt_pk_bf16_f32 v51, v51, v52
	v_cvt_pk_bf16_f32 v52, v66, v58
	v_mad_i64_i32 v[56:57], s[38:39], v70, s65, v[144:145]
	v_mul_f32_e32 v53, v54, v55
	v_cvt_pk_bf16_f32 v53, v59, v53
	global_store_dwordx4 v[72:73], v[50:53], off
	s_nop 0
	v_add_u32_e32 v54, 0xa0, v148
	v_mov_b32_e32 v50, v38
	v_mov_b32_e32 v38, v36
	v_mov_b32_e32 v52, v34
	v_mov_b32_e32 v34, v40
	v_ashrrev_i32_e32 v55, 31, v54
	v_lshl_add_u64 v[58:59], v[54:55], 2, s[14:15]
	v_lshl_add_u64 v[56:57], v[56:57], 0, s[36:37]
	v_lshl_add_u64 v[56:57], v[56:57], 0, v[146:147]
	v_mov_b32_e32 v51, v204
	v_fmamk_f32 v36, v51, 0x3a000000, v156
	v_rsq_f32_e32 v40, v36
	s_nop 0
	v_pk_mul_f32 v[46:47], v[46:47], v[40:41] op_sel_hi:[1,0]
	s_nop 0
	v_mul_f32_e32 v36, 0xbfb8aa3b, v46
	v_exp_f32_e32 v36, v36
	v_pk_mul_f32 v[42:43], v[42:43], v[40:41] op_sel_hi:[1,0]
	v_pk_mul_f32 v[48:49], v[48:49], v[40:41] op_sel_hi:[1,0]
	v_mul_f32_e32 v55, 0xbfb8aa3b, v42
	v_exp_f32_e32 v55, v55
	v_add_f32_e32 v36, 1.0, v36
	v_pk_mul_f32 v[44:45], v[44:45], v[40:41] op_sel_hi:[1,0]
	v_mov_b32_e32 v53, v42
	v_mov_b32_e32 v42, v35
	v_mul_f32_e32 v62, 0xbfb8aa3b, v48
	v_mov_b32_e32 v35, v48
	v_mov_b32_e32 v48, v41
	v_rcp_f32_e32 v41, v36
	v_mul_f32_e32 v60, 0xbfb8aa3b, v47
	v_mov_b32_e32 v51, v46
	v_exp_f32_e32 v60, v60
	v_add_f32_e32 v55, 1.0, v55
	v_mov_b32_e32 v46, v39
	v_mul_f32_e32 v63, 0xbfb8aa3b, v44
	v_mov_b32_e32 v39, v44
	v_mov_b32_e32 v44, v37
	v_pk_mul_f32 v[36:37], v[50:51], v[40:41]
	v_rcp_f32_e32 v41, v55
	v_mul_f32_e32 v61, 0xbfb8aa3b, v43
	v_exp_f32_e32 v55, v61
	v_add_f32_e32 v60, 1.0, v60
	v_pk_mul_f32 v[50:51], v[52:53], v[40:41]
	v_rcp_f32_e32 v41, v60
	v_exp_f32_e32 v61, v62
	v_add_f32_e32 v55, 1.0, v55
	v_exp_f32_e32 v52, v63
	v_pk_mul_f32 v[46:47], v[46:47], v[40:41]
	v_rcp_f32_e32 v41, v55
	v_add_f32_e32 v60, 1.0, v61
	v_mul_f32_e32 v64, 0xbfb8aa3b, v49
	v_exp_f32_e32 v53, v64
	v_pk_mul_f32 v[42:43], v[42:43], v[40:41]
	v_rcp_f32_e32 v41, v60
	v_add_f32_e32 v52, 1.0, v52
	v_mul_f32_e32 v60, v36, v37
	v_mul_f32_e32 v65, 0xbfb8aa3b, v45
	v_pk_mul_f32 v[36:37], v[34:35], v[40:41]
	v_rcp_f32_e32 v41, v52
	v_exp_f32_e32 v55, v65
	v_add_f32_e32 v53, 1.0, v53
	v_mul_f32_e32 v35, v36, v37
	v_pk_mul_f32 v[38:39], v[38:39], v[40:41]
	v_rcp_f32_e32 v41, v53
	v_add_f32_e32 v55, 1.0, v55
	v_mul_f32_e32 v42, v42, v43
	v_mul_f32_e32 v43, v38, v39
	v_pk_mul_f32 v[36:37], v[48:49], v[40:41]
	v_rcp_f32_e32 v41, v55
	v_mul_f32_e32 v34, v46, v47
	v_mul_f32_e32 v36, v36, v37
	v_mul_f32_e32 v50, v50, v51
	v_pk_mul_f32 v[38:39], v[44:45], v[40:41]
	v_cvt_pk_bf16_f32 v34, v60, v34
	v_cvt_pk_bf16_f32 v35, v35, v36
	v_cvt_pk_bf16_f32 v36, v50, v42
	v_mad_i64_i32 v[40:41], s[38:39], v54, s65, v[144:145]
	v_mul_f32_e32 v37, v38, v39
	v_cvt_pk_bf16_f32 v37, v43, v37
	global_store_dwordx4 v[56:57], v[34:37], off
	s_nop 0
	v_add_u32_e32 v38, 0xb0, v148
	v_mov_b32_e32 v34, v22
	v_mov_b32_e32 v22, v20
	v_mov_b32_e32 v36, v18
	v_mov_b32_e32 v18, v24
	v_ashrrev_i32_e32 v39, 31, v38
	v_lshl_add_u64 v[42:43], v[38:39], 2, s[14:15]
	v_lshl_add_u64 v[40:41], v[40:41], 0, s[36:37]
	v_lshl_add_u64 v[40:41], v[40:41], 0, v[146:147]
	v_mov_b32_e32 v35, v205
	v_fmamk_f32 v20, v35, 0x3a000000, v156
	v_rsq_f32_e32 v24, v20
	s_nop 0
	v_pk_mul_f32 v[30:31], v[30:31], v[24:25] op_sel_hi:[1,0]
	s_nop 0
	v_mul_f32_e32 v20, 0xbfb8aa3b, v30
	v_exp_f32_e32 v20, v20
	v_pk_mul_f32 v[26:27], v[26:27], v[24:25] op_sel_hi:[1,0]
	v_pk_mul_f32 v[32:33], v[32:33], v[24:25] op_sel_hi:[1,0]
	v_mul_f32_e32 v39, 0xbfb8aa3b, v26
	v_exp_f32_e32 v39, v39
	v_add_f32_e32 v20, 1.0, v20
	v_pk_mul_f32 v[28:29], v[28:29], v[24:25] op_sel_hi:[1,0]
	v_mov_b32_e32 v37, v26
	v_mov_b32_e32 v26, v19
	v_mul_f32_e32 v46, 0xbfb8aa3b, v32
	v_mov_b32_e32 v19, v32
	v_mov_b32_e32 v32, v25
	v_rcp_f32_e32 v25, v20
	v_mul_f32_e32 v44, 0xbfb8aa3b, v31
	v_mov_b32_e32 v35, v30
	v_exp_f32_e32 v44, v44
	v_add_f32_e32 v39, 1.0, v39
	v_mov_b32_e32 v30, v23
	v_mul_f32_e32 v47, 0xbfb8aa3b, v28
	v_mov_b32_e32 v23, v28
	v_mov_b32_e32 v28, v21
	v_pk_mul_f32 v[20:21], v[34:35], v[24:25]
	v_rcp_f32_e32 v25, v39
	v_mul_f32_e32 v45, 0xbfb8aa3b, v27
	v_exp_f32_e32 v39, v45
	v_add_f32_e32 v44, 1.0, v44
	v_pk_mul_f32 v[34:35], v[36:37], v[24:25]
	v_rcp_f32_e32 v25, v44
	v_exp_f32_e32 v45, v46
	v_add_f32_e32 v39, 1.0, v39
	v_exp_f32_e32 v36, v47
	v_pk_mul_f32 v[30:31], v[30:31], v[24:25]
	v_rcp_f32_e32 v25, v39
	v_add_f32_e32 v44, 1.0, v45
	v_mul_f32_e32 v48, 0xbfb8aa3b, v33
	v_exp_f32_e32 v37, v48
	v_pk_mul_f32 v[26:27], v[26:27], v[24:25]
	v_rcp_f32_e32 v25, v44
	v_add_f32_e32 v36, 1.0, v36
	v_mul_f32_e32 v44, v20, v21
	v_mul_f32_e32 v49, 0xbfb8aa3b, v29
	v_pk_mul_f32 v[20:21], v[18:19], v[24:25]
	v_rcp_f32_e32 v25, v36
	v_exp_f32_e32 v39, v49
	v_add_f32_e32 v37, 1.0, v37
	v_mul_f32_e32 v19, v20, v21
	v_pk_mul_f32 v[22:23], v[22:23], v[24:25]
	v_rcp_f32_e32 v25, v37
	v_add_f32_e32 v39, 1.0, v39
	v_mul_f32_e32 v26, v26, v27
	v_mul_f32_e32 v27, v22, v23
	v_pk_mul_f32 v[20:21], v[32:33], v[24:25]
	v_rcp_f32_e32 v25, v39
	v_mul_f32_e32 v18, v30, v31
	v_mul_f32_e32 v20, v20, v21
	v_mul_f32_e32 v34, v34, v35
	v_pk_mul_f32 v[22:23], v[28:29], v[24:25]
	v_cvt_pk_bf16_f32 v18, v44, v18
	v_cvt_pk_bf16_f32 v19, v19, v20
	v_cvt_pk_bf16_f32 v20, v34, v26
	s_nop 0
	v_mul_f32_e32 v21, v22, v23
	v_cvt_pk_bf16_f32 v21, v27, v21
	global_store_dwordx4 v[40:41], v[18:21], off
	s_nop 0
	v_mad_i64_i32 v[22:23], s[0:1], v38, s65, v[144:145]
	v_mov_b32_e32 v18, v6
	v_mov_b32_e32 v6, v4
	v_mov_b32_e32 v20, v2
	v_mov_b32_e32 v2, v8
	v_lshl_add_u64 v[22:23], v[22:23], 0, s[36:37]
	v_lshl_add_u64 v[22:23], v[22:23], 0, v[146:147]
	s_mov_b64 s[0:1], -1
	v_mov_b32_e32 v19, v206
	v_fmamk_f32 v4, v19, 0x3a000000, v156
	v_rsq_f32_e32 v8, v4
	s_nop 0
	v_pk_mul_f32 v[14:15], v[14:15], v[8:9] op_sel_hi:[1,0]
	s_nop 0
	v_mul_f32_e32 v4, 0xbfb8aa3b, v14
	v_exp_f32_e32 v4, v4
	v_pk_mul_f32 v[10:11], v[10:11], v[8:9] op_sel_hi:[1,0]
	v_pk_mul_f32 v[16:17], v[16:17], v[8:9] op_sel_hi:[1,0]
	v_mul_f32_e32 v24, 0xbfb8aa3b, v10
	v_exp_f32_e32 v24, v24
	v_add_f32_e32 v4, 1.0, v4
	v_pk_mul_f32 v[12:13], v[12:13], v[8:9] op_sel_hi:[1,0]
	v_mov_b32_e32 v21, v10
	v_mov_b32_e32 v10, v3
	v_mul_f32_e32 v27, 0xbfb8aa3b, v16
	v_mov_b32_e32 v3, v16
	v_mov_b32_e32 v16, v9
	v_rcp_f32_e32 v9, v4
	v_mul_f32_e32 v25, 0xbfb8aa3b, v15
	v_mov_b32_e32 v19, v14
	v_exp_f32_e32 v25, v25
	v_add_f32_e32 v24, 1.0, v24
	v_mov_b32_e32 v14, v7
	v_mul_f32_e32 v28, 0xbfb8aa3b, v12
	v_mov_b32_e32 v7, v12
	v_mov_b32_e32 v12, v5
	v_pk_mul_f32 v[4:5], v[18:19], v[8:9]
	v_rcp_f32_e32 v9, v24
	v_mul_f32_e32 v26, 0xbfb8aa3b, v11
	v_exp_f32_e32 v24, v26
	v_add_f32_e32 v25, 1.0, v25
	v_pk_mul_f32 v[18:19], v[20:21], v[8:9]
	v_rcp_f32_e32 v9, v25
	v_exp_f32_e32 v26, v27
	v_add_f32_e32 v24, 1.0, v24
	v_exp_f32_e32 v20, v28
	v_pk_mul_f32 v[14:15], v[14:15], v[8:9]
	v_rcp_f32_e32 v9, v24
	v_add_f32_e32 v25, 1.0, v26
	v_mul_f32_e32 v29, 0xbfb8aa3b, v17
	v_exp_f32_e32 v21, v29
	v_pk_mul_f32 v[10:11], v[10:11], v[8:9]
	v_rcp_f32_e32 v9, v25
	v_add_f32_e32 v20, 1.0, v20
	v_mul_f32_e32 v25, v4, v5
	v_mul_f32_e32 v30, 0xbfb8aa3b, v13
	v_pk_mul_f32 v[4:5], v[2:3], v[8:9]
	v_rcp_f32_e32 v9, v20
	v_exp_f32_e32 v24, v30
	v_add_f32_e32 v21, 1.0, v21
	v_mul_f32_e32 v3, v4, v5
	v_pk_mul_f32 v[6:7], v[6:7], v[8:9]
	v_rcp_f32_e32 v9, v21
	v_add_f32_e32 v24, 1.0, v24
	v_mul_f32_e32 v10, v10, v11
	v_mul_f32_e32 v11, v6, v7
	v_pk_mul_f32 v[4:5], v[16:17], v[8:9]
	v_rcp_f32_e32 v9, v24
	v_mul_f32_e32 v2, v14, v15
	v_mul_f32_e32 v4, v4, v5
	v_mul_f32_e32 v18, v18, v19
	v_pk_mul_f32 v[6:7], v[12:13], v[8:9]
	v_cvt_pk_bf16_f32 v2, v25, v2
	v_cvt_pk_bf16_f32 v3, v3, v4
	v_cvt_pk_bf16_f32 v4, v18, v10
	s_nop 0
	v_mul_f32_e32 v5, v6, v7
	v_cvt_pk_bf16_f32 v5, v11, v5
	global_store_dwordx4 v[22:23], v[2:5], off
	s_cbranch_vccnz .LBB0_1186
	s_andn2_b64 vcc, exec, s[12:13]
	s_cbranch_vccnz .LBB0_1185
	s_barrier
	s_branch .LBB0_1185

.LBB0_1476:
	v_lshlrev_b64 v[140:141], 2, v[140:141]
	v_lshl_add_u64 v[10:11], s[74:75], 0, v[140:141]
	global_load_dwordx4 v[6:9], v[10:11], off offset:16
	global_load_dwordx4 v[14:17], v[10:11], off
	global_load_dwordx4 v[2:5], v[10:11], off offset:528
	s_nop 0
	global_load_dwordx4 v[10:13], v[10:11], off offset:512
	s_nop 0
	global_load_dword v138, v[146:147], off sc1
	global_load_dword v224, v[152:153], off sc1
	global_load_dword v225, v[156:157], off sc1
	global_load_dword v226, v[160:161], off sc1
	global_load_dword v227, v[164:165], off sc1
	global_load_dword v228, v[168:169], off sc1
	global_load_dword v229, v[172:173], off sc1
	global_load_dword v230, v[188:189], off sc1
	v_lshlrev_b64 v[142:143], 13, v[142:143]
	v_lshl_add_u64 v[142:143], s[28:29], 0, v[142:143]
	v_lshl_add_u64 v[142:143], v[142:143], 0, v[140:141]
	s_and_b64 vcc, exec, s[4:5]
	s_mov_b64 s[0:1], -1
	s_waitcnt vmcnt(0) lgkmcnt(0)
	v_fmamk_f32 v138, v138, 0x3a000000, v198
	v_rsq_f32_e32 v138, v138
	s_nop 0
	v_pk_mul_f32 v[126:127], v[126:127], v[138:139] op_sel_hi:[1,0]
	v_pk_mul_f32 v[124:125], v[124:125], v[138:139] op_sel_hi:[1,0]
	v_pk_mul_f32 v[122:123], v[122:123], v[138:139] op_sel_hi:[1,0]
	v_pk_mul_f32 v[120:121], v[120:121], v[138:139] op_sel_hi:[1,0]
	v_pk_mul_f32 v[146:147], v[118:119], v[138:139] op_sel_hi:[1,0]
	v_pk_mul_f32 v[200:201], v[116:117], v[138:139] op_sel_hi:[1,0]
	v_pk_mul_f32 v[202:203], v[114:115], v[138:139] op_sel_hi:[1,0]
	v_pk_mul_f32 v[128:129], v[128:129], v[138:139] op_sel_hi:[1,0]
	v_pk_mul_f32 v[116:117], v[16:17], v[124:125]
	v_pk_mul_f32 v[114:115], v[14:15], v[126:127]
	v_pk_mul_f32 v[120:121], v[8:9], v[120:121]
	v_pk_mul_f32 v[118:119], v[6:7], v[122:123]
	v_pk_mul_f32 v[124:125], v[12:13], v[200:201]
	v_pk_mul_f32 v[122:123], v[10:11], v[146:147]
	v_pk_mul_f32 v[128:129], v[4:5], v[128:129]
	v_pk_mul_f32 v[126:127], v[2:3], v[202:203]
	global_store_dwordx4 v[142:143], v[114:117], off
	global_store_dwordx4 v[142:143], v[118:121], off offset:16
	global_store_dwordx4 v[142:143], v[122:125], off offset:512
	global_store_dwordx4 v[142:143], v[126:129], off offset:528
	s_nop 0
	v_lshlrev_b64 v[116:117], 13, v[144:145]
	v_lshl_add_u64 v[116:117], s[28:29], 0, v[116:117]
	v_lshl_add_u64 v[116:117], v[116:117], 0, v[140:141]
	v_mov_b32_e32 v114, v224
	v_fmamk_f32 v114, v114, 0x3a000000, v198
	v_rsq_f32_e32 v114, v114
	s_nop 0
	v_pk_mul_f32 v[108:109], v[108:109], v[114:115] op_sel_hi:[1,0]
	v_pk_mul_f32 v[110:111], v[110:111], v[114:115] op_sel_hi:[1,0]
	v_pk_mul_f32 v[106:107], v[106:107], v[114:115] op_sel_hi:[1,0]
	v_pk_mul_f32 v[104:105], v[104:105], v[114:115] op_sel_hi:[1,0]
	v_pk_mul_f32 v[118:119], v[102:103], v[114:115] op_sel_hi:[1,0]
	v_pk_mul_f32 v[120:121], v[100:101], v[114:115] op_sel_hi:[1,0]
	v_pk_mul_f32 v[122:123], v[98:99], v[114:115] op_sel_hi:[1,0]
	v_pk_mul_f32 v[112:113], v[112:113], v[114:115] op_sel_hi:[1,0]
	v_pk_mul_f32 v[100:101], v[16:17], v[110:111]
	v_pk_mul_f32 v[98:99], v[14:15], v[108:109]
	v_pk_mul_f32 v[104:105], v[8:9], v[104:105]
	v_pk_mul_f32 v[102:103], v[6:7], v[106:107]
	v_pk_mul_f32 v[108:109], v[12:13], v[120:121]
	v_pk_mul_f32 v[106:107], v[10:11], v[118:119]
	v_pk_mul_f32 v[112:113], v[4:5], v[112:113]
	v_pk_mul_f32 v[110:111], v[2:3], v[122:123]
	global_store_dwordx4 v[116:117], v[98:101], off
	global_store_dwordx4 v[116:117], v[102:105], off offset:16
	global_store_dwordx4 v[116:117], v[106:109], off offset:512
	global_store_dwordx4 v[116:117], v[110:113], off offset:528
	s_nop 0
	v_lshlrev_b64 v[100:101], 13, v[150:151]
	v_lshl_add_u64 v[100:101], s[28:29], 0, v[100:101]
	v_lshl_add_u64 v[100:101], v[100:101], 0, v[140:141]
	v_mov_b32_e32 v98, v225
	v_fmamk_f32 v98, v98, 0x3a000000, v198
	v_rsq_f32_e32 v98, v98
	s_nop 0
	v_pk_mul_f32 v[92:93], v[92:93], v[98:99] op_sel_hi:[1,0]
	v_pk_mul_f32 v[94:95], v[94:95], v[98:99] op_sel_hi:[1,0]
	v_pk_mul_f32 v[90:91], v[90:91], v[98:99] op_sel_hi:[1,0]
	v_pk_mul_f32 v[88:89], v[88:89], v[98:99] op_sel_hi:[1,0]
	v_pk_mul_f32 v[102:103], v[86:87], v[98:99] op_sel_hi:[1,0]
	v_pk_mul_f32 v[104:105], v[84:85], v[98:99] op_sel_hi:[1,0]
	v_pk_mul_f32 v[106:107], v[82:83], v[98:99] op_sel_hi:[1,0]
	v_pk_mul_f32 v[96:97], v[96:97], v[98:99] op_sel_hi:[1,0]
	v_pk_mul_f32 v[84:85], v[16:17], v[94:95]
	v_pk_mul_f32 v[82:83], v[14:15], v[92:93]
	v_pk_mul_f32 v[88:89], v[8:9], v[88:89]
	v_pk_mul_f32 v[86:87], v[6:7], v[90:91]
	v_pk_mul_f32 v[92:93], v[12:13], v[104:105]
	v_pk_mul_f32 v[90:91], v[10:11], v[102:103]
	v_pk_mul_f32 v[96:97], v[4:5], v[96:97]
	v_pk_mul_f32 v[94:95], v[2:3], v[106:107]
	global_store_dwordx4 v[100:101], v[82:85], off
	global_store_dwordx4 v[100:101], v[86:89], off offset:16
	global_store_dwordx4 v[100:101], v[90:93], off offset:512
	global_store_dwordx4 v[100:101], v[94:97], off offset:528
	s_nop 0
	v_lshlrev_b64 v[84:85], 13, v[154:155]
	v_lshl_add_u64 v[84:85], s[28:29], 0, v[84:85]
	v_lshl_add_u64 v[84:85], v[84:85], 0, v[140:141]
	v_mov_b32_e32 v82, v226
	v_fmamk_f32 v82, v82, 0x3a000000, v198
	v_rsq_f32_e32 v82, v82
	s_nop 0
	v_pk_mul_f32 v[76:77], v[76:77], v[82:83] op_sel_hi:[1,0]
	v_pk_mul_f32 v[78:79], v[78:79], v[82:83] op_sel_hi:[1,0]
	v_pk_mul_f32 v[74:75], v[74:75], v[82:83] op_sel_hi:[1,0]
	v_pk_mul_f32 v[72:73], v[72:73], v[82:83] op_sel_hi:[1,0]
	v_pk_mul_f32 v[86:87], v[70:71], v[82:83] op_sel_hi:[1,0]
	v_pk_mul_f32 v[88:89], v[68:69], v[82:83] op_sel_hi:[1,0]
	v_pk_mul_f32 v[90:91], v[66:67], v[82:83] op_sel_hi:[1,0]
	v_pk_mul_f32 v[80:81], v[80:81], v[82:83] op_sel_hi:[1,0]
	v_pk_mul_f32 v[68:69], v[16:17], v[78:79]
	v_pk_mul_f32 v[66:67], v[14:15], v[76:77]
	v_pk_mul_f32 v[72:73], v[8:9], v[72:73]
	v_pk_mul_f32 v[70:71], v[6:7], v[74:75]
	v_pk_mul_f32 v[76:77], v[12:13], v[88:89]
	v_pk_mul_f32 v[74:75], v[10:11], v[86:87]
	v_pk_mul_f32 v[80:81], v[4:5], v[80:81]
	v_pk_mul_f32 v[78:79], v[2:3], v[90:91]
	global_store_dwordx4 v[84:85], v[66:69], off
	global_store_dwordx4 v[84:85], v[70:73], off offset:16
	global_store_dwordx4 v[84:85], v[74:77], off offset:512
	global_store_dwordx4 v[84:85], v[78:81], off offset:528
	s_nop 0
	v_lshlrev_b64 v[68:69], 13, v[158:159]
	v_lshl_add_u64 v[68:69], s[28:29], 0, v[68:69]
	v_lshl_add_u64 v[68:69], v[68:69], 0, v[140:141]
	v_mov_b32_e32 v66, v227
	v_fmamk_f32 v66, v66, 0x3a000000, v198
	v_rsq_f32_e32 v66, v66
	s_nop 0
	v_pk_mul_f32 v[60:61], v[60:61], v[66:67] op_sel_hi:[1,0]
	v_pk_mul_f32 v[62:63], v[62:63], v[66:67] op_sel_hi:[1,0]
	v_pk_mul_f32 v[58:59], v[58:59], v[66:67] op_sel_hi:[1,0]
	v_pk_mul_f32 v[56:57], v[56:57], v[66:67] op_sel_hi:[1,0]
	v_pk_mul_f32 v[70:71], v[54:55], v[66:67] op_sel_hi:[1,0]
	v_pk_mul_f32 v[72:73], v[52:53], v[66:67] op_sel_hi:[1,0]
	v_pk_mul_f32 v[74:75], v[50:51], v[66:67] op_sel_hi:[1,0]
	v_pk_mul_f32 v[64:65], v[64:65], v[66:67] op_sel_hi:[1,0]
	v_pk_mul_f32 v[52:53], v[16:17], v[62:63]
	v_pk_mul_f32 v[50:51], v[14:15], v[60:61]
	v_pk_mul_f32 v[56:57], v[8:9], v[56:57]
	v_pk_mul_f32 v[54:55], v[6:7], v[58:59]
	v_pk_mul_f32 v[60:61], v[12:13], v[72:73]
	v_pk_mul_f32 v[58:59], v[10:11], v[70:71]
	v_pk_mul_f32 v[64:65], v[4:5], v[64:65]
	v_pk_mul_f32 v[62:63], v[2:3], v[74:75]
	global_store_dwordx4 v[68:69], v[50:53], off
	global_store_dwordx4 v[68:69], v[54:57], off offset:16
	global_store_dwordx4 v[68:69], v[58:61], off offset:512
	global_store_dwordx4 v[68:69], v[62:65], off offset:528
	s_nop 0
	v_lshlrev_b64 v[52:53], 13, v[162:163]
	v_lshl_add_u64 v[52:53], s[28:29], 0, v[52:53]
	v_lshl_add_u64 v[52:53], v[52:53], 0, v[140:141]
	v_mov_b32_e32 v50, v228
	v_fmamk_f32 v50, v50, 0x3a000000, v198
	v_rsq_f32_e32 v50, v50
	s_nop 0
	v_pk_mul_f32 v[44:45], v[44:45], v[50:51] op_sel_hi:[1,0]
	v_pk_mul_f32 v[46:47], v[46:47], v[50:51] op_sel_hi:[1,0]
	v_pk_mul_f32 v[42:43], v[42:43], v[50:51] op_sel_hi:[1,0]
	v_pk_mul_f32 v[40:41], v[40:41], v[50:51] op_sel_hi:[1,0]
	v_pk_mul_f32 v[54:55], v[38:39], v[50:51] op_sel_hi:[1,0]
	v_pk_mul_f32 v[56:57], v[36:37], v[50:51] op_sel_hi:[1,0]
	v_pk_mul_f32 v[58:59], v[34:35], v[50:51] op_sel_hi:[1,0]
	v_pk_mul_f32 v[48:49], v[48:49], v[50:51] op_sel_hi:[1,0]
	v_pk_mul_f32 v[36:37], v[16:17], v[46:47]
	v_pk_mul_f32 v[34:35], v[14:15], v[44:45]
	v_pk_mul_f32 v[40:41], v[8:9], v[40:41]
	v_pk_mul_f32 v[38:39], v[6:7], v[42:43]
	v_pk_mul_f32 v[44:45], v[12:13], v[56:57]
	v_pk_mul_f32 v[42:43], v[10:11], v[54:55]
	v_pk_mul_f32 v[48:49], v[4:5], v[48:49]
	v_pk_mul_f32 v[46:47], v[2:3], v[58:59]
	global_store_dwordx4 v[52:53], v[34:37], off
	global_store_dwordx4 v[52:53], v[38:41], off offset:16
	global_store_dwordx4 v[52:53], v[42:45], off offset:512
	global_store_dwordx4 v[52:53], v[46:49], off offset:528
	s_nop 0
	v_lshlrev_b64 v[36:37], 13, v[166:167]
	v_lshl_add_u64 v[36:37], s[28:29], 0, v[36:37]
	v_lshl_add_u64 v[36:37], v[36:37], 0, v[140:141]
	v_mov_b32_e32 v34, v229
	v_fmamk_f32 v34, v34, 0x3a000000, v198
	v_rsq_f32_e32 v34, v34
	s_nop 0
	v_pk_mul_f32 v[28:29], v[28:29], v[34:35] op_sel_hi:[1,0]
	v_pk_mul_f32 v[30:31], v[30:31], v[34:35] op_sel_hi:[1,0]
	v_pk_mul_f32 v[26:27], v[26:27], v[34:35] op_sel_hi:[1,0]
	v_pk_mul_f32 v[24:25], v[24:25], v[34:35] op_sel_hi:[1,0]
	v_pk_mul_f32 v[38:39], v[22:23], v[34:35] op_sel_hi:[1,0]
	v_pk_mul_f32 v[40:41], v[20:21], v[34:35] op_sel_hi:[1,0]
	v_pk_mul_f32 v[42:43], v[18:19], v[34:35] op_sel_hi:[1,0]
	v_pk_mul_f32 v[32:33], v[32:33], v[34:35] op_sel_hi:[1,0]
	v_pk_mul_f32 v[20:21], v[16:17], v[30:31]
	v_pk_mul_f32 v[18:19], v[14:15], v[28:29]
	v_pk_mul_f32 v[24:25], v[8:9], v[24:25]
	v_pk_mul_f32 v[22:23], v[6:7], v[26:27]
	v_pk_mul_f32 v[28:29], v[12:13], v[40:41]
	v_pk_mul_f32 v[26:27], v[10:11], v[38:39]
	v_pk_mul_f32 v[32:33], v[4:5], v[32:33]
	v_pk_mul_f32 v[30:31], v[2:3], v[42:43]
	global_store_dwordx4 v[36:37], v[18:21], off
	global_store_dwordx4 v[36:37], v[22:25], off offset:16
	global_store_dwordx4 v[36:37], v[26:29], off offset:512
	global_store_dwordx4 v[36:37], v[30:33], off offset:528
	s_nop 0
	v_lshlrev_b64 v[18:19], 13, v[170:171]
	v_lshl_add_u64 v[18:19], s[28:29], 0, v[18:19]
	v_lshl_add_u64 v[18:19], v[18:19], 0, v[140:141]
	v_mov_b32_e32 v20, v230
	v_fmamk_f32 v20, v20, 0x3a000000, v198
	v_rsq_f32_e32 v20, v20
	s_nop 0
	v_pk_mul_f32 v[22:23], v[178:179], v[20:21] op_sel_hi:[1,0]
	v_pk_mul_f32 v[24:25], v[180:181], v[20:21] op_sel_hi:[1,0]
	v_pk_mul_f32 v[26:27], v[176:177], v[20:21] op_sel_hi:[1,0]
	v_pk_mul_f32 v[28:29], v[182:183], v[20:21] op_sel_hi:[1,0]
	v_pk_mul_f32 v[30:31], v[174:175], v[20:21] op_sel_hi:[1,0]
	v_pk_mul_f32 v[32:33], v[184:185], v[20:21] op_sel_hi:[1,0]
	v_pk_mul_f32 v[34:35], v[148:149], v[20:21] op_sel_hi:[1,0]
	v_pk_mul_f32 v[20:21], v[186:187], v[20:21] op_sel_hi:[1,0]
	v_pk_mul_f32 v[16:17], v[16:17], v[24:25]
	v_pk_mul_f32 v[14:15], v[14:15], v[22:23]
	v_pk_mul_f32 v[8:9], v[8:9], v[28:29]
	v_pk_mul_f32 v[6:7], v[6:7], v[26:27]
	v_pk_mul_f32 v[12:13], v[12:13], v[32:33]
	v_pk_mul_f32 v[10:11], v[10:11], v[30:31]
	v_pk_mul_f32 v[4:5], v[4:5], v[20:21]
	v_pk_mul_f32 v[2:3], v[2:3], v[34:35]
	global_store_dwordx4 v[18:19], v[14:17], off
	global_store_dwordx4 v[18:19], v[6:9], off offset:16
	global_store_dwordx4 v[18:19], v[10:13], off offset:512
	global_store_dwordx4 v[18:19], v[2:5], off offset:528
	s_cbranch_vccnz .LBB0_1441
	s_andn2_b64 vcc, exec, s[38:39]
	s_cbranch_vccnz .LBB0_1440
	s_barrier
	s_branch .LBB0_1440
